# GEMM main loops (in-proj, merge, out-proj): the second s_waitcnt lgkmcnt(0) after each barrier+setprio deleted (already zero: the wait before the barrier covers it); 12 sites
# speedup vs baseline: 1.0158x; 1.0015x over previous
; #define PG8_STAGE(bufoff, gbase, voff) do { _Pragma("unroll") for (int _i = 0; _i < 2; ++_i) \
;         __builtin_amdgcn_global_load_lds((const unsigned*)((const char*)(gbase) + (voff)[_i]), (PG8_LAS unsigned*)(lds + (bufoff) + ldsw + _i * 8192), 16, 0, 0); } while (0)
; #define PG8_LDA(dst, b, h) do { _Pragma("unroll") for (int m = 0; m < 4; ++m) _Pragma("unroll") for (int k = 0; k < 2; ++k) dst[m][k] = *(const PG8_LAS bf16x8*)(lds + PG8_SA(b, h) + aoff + m * 2048 + k * 1024); } while (0)
; #define PG8_LDB(dst, b, h) do { _Pragma("unroll") for (int n = 0; n < 2; ++n) _Pragma("unroll") for (int k = 0; k < 2; ++k) dst[n][k] = *(const PG8_LAS bf16x8*)(lds + PG8_SB(b, h) + boff + n * 2048 + k * 1024); } while (0)
; #define PG8_MMA(ai, bj, At, Bt) do { __builtin_amdgcn_s_setprio(1); _Pragma("unroll") for (int m = 0; m < 4; ++m) _Pragma("unroll") for (int n = 0; n < 2; ++n) _Pragma("unroll") for (int k = 0; k < 2; ++k) \
;         acc[ai][bj][m][n] = __builtin_amdgcn_mfma_f32_16x16x32_bf16(Bt[n][k], At[m][k], acc[ai][bj][m][n], 0, 0, 0); __builtin_amdgcn_s_setprio(0); } while (0)
; #define PG8_WAIT_V(n) asm volatile("s_waitcnt vmcnt(" #n ")" ::: "memory")
; #define PG8_WAIT_L(n) asm volatile("s_waitcnt lgkmcnt(" #n ")" ::: "memory")
; #define PG8_BAR __builtin_amdgcn_s_barrier()
; #define PG8_SCHED __builtin_amdgcn_sched_barrier(0)
; template <class Epi, class Sched, bool ALIGN_EPI = false, bool SP2 = false>
; __device__ __forceinline__ void gemm_phase(PG8_LAS unsigned char* lds, const Gemm g, const Sched& S, const Epi& E) {
;     ...
;             PG8_LDB(B0, 0, 0); PG8_LDB(B1, 0, 1); PG8_SCHED; PG8_LDA(At, 0, 0); PG8_STAGE(PG8_SA(1, 1), a1 + hstep, voffA);
;             PG8_WAIT_V(8); PG8_WAIT_L(0); PG8_BAR; PG8_MMA(0, 0, At, B0); PG8_MMA(0, 1, At, B1); PG8_BAR; PG8_SCHED;
;             PG8_LDA(At, 0, 1); PG8_STAGE(PG8_SB(0, 0), b2, voffB); PG8_STAGE(PG8_SB(0, 1), b2 + hstep, voffB); PG8_STAGE(PG8_SA(0, 0), a2, voffA);
;             PG8_WAIT_V(8); PG8_WAIT_L(0); PG8_BAR; PG8_MMA(1, 0, At, B0); PG8_MMA(1, 1, At, B1); PG8_BAR; PG8_SCHED;
.LBB0_161:
	s_add_u32 s8, s6, 0xfff80080
	s_addc_u32 s9, s7, -1
	s_add_i32 s93, 0, 0x10000
	s_cmp_eq_u32 s85, 28
	s_cselect_b32 s11, s15, s9
	s_cselect_b32 s10, s29, s8
	v_add_u32_e32 v151, s93, v135
	s_cselect_b32 s9, s45, s84
	s_cselect_b32 s8, s60, s73
	s_add_i32 s97, 0, 0x14000
	ds_read_b128 v[152:155], v151
	ds_read_b128 v[156:159], v151 offset:1024
	ds_read_b128 v[160:163], v151 offset:2048
	ds_read_b128 v[164:167], v151 offset:3072
	v_add_u32_e32 v151, s97, v135
	ds_read_b128 v[168:171], v151
	ds_read_b128 v[172:175], v151 offset:1024
	ds_read_b128 v[180:183], v151 offset:2048
	ds_read_b128 v[184:187], v151 offset:3072
	v_lshl_add_u64 v[196:197], s[6:7], 0, v[146:147]
	s_add_i32 m0, s90, 0xc000
	ds_read_b128 v[188:191], v178
	ds_read_b128 v[192:195], v178 offset:1024
	ds_read_b128 v[200:203], v178 offset:2048
	ds_read_b128 v[204:207], v178 offset:3072
	ds_read_b128 v[208:211], v178 offset:4096
	ds_read_b128 v[212:215], v178 offset:5120
	ds_read_b128 v[216:219], v178 offset:6144
	ds_read_b128 v[236:239], v178 offset:7168
	global_load_lds_dwordx4 v[196:197], off
	v_lshl_add_u64 v[196:197], s[6:7], 0, v[148:149]
	s_add_i32 m0, s90, 0xe000
	s_nop 0
	global_load_lds_dwordx4 v[196:197], off
	s_waitcnt vmcnt(8)
	s_waitcnt lgkmcnt(0)
	s_barrier
	s_setprio 1
	v_mfma_f32_16x16x32_bf16 v[130:133], v[152:155], v[188:191], v[130:133]
	v_mfma_f32_16x16x32_bf16 v[126:129], v[160:163], v[188:191], v[126:129]
	v_mfma_f32_16x16x32_bf16 v[114:117], v[152:155], v[200:203], v[114:117]
	v_mfma_f32_16x16x32_bf16 v[110:113], v[160:163], v[200:203], v[110:113]
	v_mfma_f32_16x16x32_bf16 v[98:101], v[152:155], v[208:211], v[98:101]
	v_mfma_f32_16x16x32_bf16 v[94:97], v[160:163], v[208:211], v[94:97]
	v_mfma_f32_16x16x32_bf16 v[82:85], v[152:155], v[216:219], v[82:85]
	v_mfma_f32_16x16x32_bf16 v[78:81], v[160:163], v[216:219], v[78:81]
	v_mfma_f32_16x16x32_bf16 v[130:133], v[156:159], v[192:195], v[130:133]
	v_mfma_f32_16x16x32_bf16 v[126:129], v[164:167], v[192:195], v[126:129]
	v_mfma_f32_16x16x32_bf16 v[114:117], v[156:159], v[204:207], v[114:117]
	v_mfma_f32_16x16x32_bf16 v[110:113], v[164:167], v[204:207], v[110:113]
	v_mfma_f32_16x16x32_bf16 v[98:101], v[156:159], v[212:215], v[98:101]
	v_mfma_f32_16x16x32_bf16 v[94:97], v[164:167], v[212:215], v[94:97]
	v_mfma_f32_16x16x32_bf16 v[82:85], v[156:159], v[236:239], v[82:85]
	v_mfma_f32_16x16x32_bf16 v[78:81], v[164:167], v[236:239], v[78:81]
	s_setprio 0
	s_setprio 1
	v_mfma_f32_16x16x32_bf16 v[122:125], v[168:171], v[188:191], v[122:125]
	v_mfma_f32_16x16x32_bf16 v[118:121], v[180:183], v[188:191], v[118:121]
	v_mfma_f32_16x16x32_bf16 v[106:109], v[168:171], v[200:203], v[106:109]
	v_mfma_f32_16x16x32_bf16 v[102:105], v[180:183], v[200:203], v[102:105]
	v_mfma_f32_16x16x32_bf16 v[90:93], v[168:171], v[208:211], v[90:93]
	v_mfma_f32_16x16x32_bf16 v[86:89], v[180:183], v[208:211], v[86:89]
	v_mfma_f32_16x16x32_bf16 v[74:77], v[168:171], v[216:219], v[74:77]
	v_mfma_f32_16x16x32_bf16 v[70:73], v[180:183], v[216:219], v[70:73]
	v_mfma_f32_16x16x32_bf16 v[122:125], v[172:175], v[192:195], v[122:125]
	v_mfma_f32_16x16x32_bf16 v[118:121], v[184:187], v[192:195], v[118:121]
	v_mfma_f32_16x16x32_bf16 v[106:109], v[172:175], v[204:207], v[106:109]
	v_mfma_f32_16x16x32_bf16 v[102:105], v[184:187], v[204:207], v[102:105]
	v_mfma_f32_16x16x32_bf16 v[90:93], v[172:175], v[212:215], v[90:93]
	v_mfma_f32_16x16x32_bf16 v[86:89], v[184:187], v[212:215], v[86:89]
	v_mfma_f32_16x16x32_bf16 v[74:77], v[172:175], v[236:239], v[74:77]
	v_mfma_f32_16x16x32_bf16 v[70:73], v[184:187], v[236:239], v[70:73]
	s_setprio 0
	s_barrier
	s_add_i32 s93, s93, s89
	v_lshl_add_u64 v[196:197], s[8:9], 0, v[142:143]
	s_mov_b32 m0, s93
	ds_read_b128 v[188:191], v178 offset:16384
	ds_read_b128 v[192:195], v178 offset:17408
	ds_read_b128 v[200:203], v178 offset:18432
	ds_read_b128 v[204:207], v178 offset:19456
	ds_read_b128 v[208:211], v178 offset:20480
	ds_read_b128 v[212:215], v178 offset:21504
	ds_read_b128 v[216:219], v178 offset:22528
	ds_read_b128 v[236:239], v178 offset:23552
	global_load_lds_dwordx4 v[196:197], off
	s_add_i32 m0, s93, 0x2000
	s_add_u32 vcc_lo, s8, 0x80000
	v_lshl_add_u64 v[228:229], s[8:9], 0, v[2:3]
	s_addc_u32 vcc_hi, s9, 0
	s_add_i32 s93, s97, s89
	global_load_lds_dwordx4 v[228:229], off
	v_lshl_add_u64 v[230:231], vcc, 0, v[142:143]
	s_mov_b32 m0, s93
	v_lshl_add_u64 v[240:241], s[10:11], 0, v[136:137]
	global_load_lds_dwordx4 v[230:231], off
	v_lshl_add_u64 v[230:231], vcc, 0, v[2:3]
	s_add_i32 m0, s93, 0x2000
	s_nop 0
	global_load_lds_dwordx4 v[230:231], off
	v_lshl_add_u64 v[230:231], s[10:11], 0, v[144:145]
	s_mov_b32 m0, s90
	s_nop 0
	global_load_lds_dwordx4 v[230:231], off
	s_mov_b32 m0, s91
	s_nop 0
	global_load_lds_dwordx4 v[240:241], off
	s_waitcnt vmcnt(8)
	s_waitcnt lgkmcnt(0)
	s_barrier
; #define PG8_STAGE(bufoff, gbase, voff) do { _Pragma("unroll") for (int _i = 0; _i < 2; ++_i) \
;         __builtin_amdgcn_global_load_lds((const unsigned*)((const char*)(gbase) + (voff)[_i]), (PG8_LAS unsigned*)(lds + (bufoff) + ldsw + _i * 8192), 16, 0, 0); } while (0)
; #define PG8_LDA(dst, b, h) do { _Pragma("unroll") for (int m = 0; m < 4; ++m) _Pragma("unroll") for (int k = 0; k < 2; ++k) dst[m][k] = *(const PG8_LAS bf16x8*)(lds + PG8_SA(b, h) + aoff + m * 2048 + k * 1024); } while (0)
; #define PG8_LDB(dst, b, h) do { _Pragma("unroll") for (int n = 0; n < 2; ++n) _Pragma("unroll") for (int k = 0; k < 2; ++k) dst[n][k] = *(const PG8_LAS bf16x8*)(lds + PG8_SB(b, h) + boff + n * 2048 + k * 1024); } while (0)
; #define PG8_MMA(ai, bj, At, Bt) do { __builtin_amdgcn_s_setprio(1); _Pragma("unroll") for (int m = 0; m < 4; ++m) _Pragma("unroll") for (int n = 0; n < 2; ++n) _Pragma("unroll") for (int k = 0; k < 2; ++k) \
;         acc[ai][bj][m][n] = __builtin_amdgcn_mfma_f32_16x16x32_bf16(Bt[n][k], At[m][k], acc[ai][bj][m][n], 0, 0, 0); __builtin_amdgcn_s_setprio(0); } while (0)
; #define PG8_WAIT_V(n) asm volatile("s_waitcnt vmcnt(" #n ")" ::: "memory")
; #define PG8_WAIT_L(n) asm volatile("s_waitcnt lgkmcnt(" #n ")" ::: "memory")
; #define PG8_BAR __builtin_amdgcn_s_barrier()
; #define PG8_SCHED __builtin_amdgcn_sched_barrier(0)
; template <class Epi, class Sched, bool ALIGN_EPI = false, bool SP2 = false>
; __device__ __forceinline__ void gemm_phase(PG8_LAS unsigned char* lds, const Gemm g, const Sched& S, const Epi& E) {
;     ...
;             PG8_WAIT_V(8); PG8_WAIT_L(0); PG8_BAR; PG8_MMA(1, 0, At, B0); PG8_MMA(1, 1, At, B1); PG8_BAR; PG8_SCHED;
;             PG8_LDB(B0, 1, 0); PG8_LDB(B1, 1, 1); PG8_SCHED; PG8_LDA(At, 1, 0); PG8_STAGE(PG8_SA(0, 1), a2 + hstep, voffA);
;             PG8_WAIT_V(8); PG8_WAIT_L(0); PG8_BAR; PG8_MMA(0, 0, At, B0); PG8_MMA(0, 1, At, B1); PG8_BAR; PG8_SCHED;
	s_setprio 1
	v_mfma_f32_16x16x32_bf16 v[66:69], v[152:155], v[188:191], v[66:69]
	v_mfma_f32_16x16x32_bf16 v[62:65], v[160:163], v[188:191], v[62:65]
	v_mfma_f32_16x16x32_bf16 v[50:53], v[152:155], v[200:203], v[50:53]
	v_mfma_f32_16x16x32_bf16 v[46:49], v[160:163], v[200:203], v[46:49]
	v_mfma_f32_16x16x32_bf16 v[34:37], v[152:155], v[208:211], v[34:37]
	v_mfma_f32_16x16x32_bf16 v[30:33], v[160:163], v[208:211], v[30:33]
	v_mfma_f32_16x16x32_bf16 v[18:21], v[152:155], v[216:219], v[18:21]
	v_mfma_f32_16x16x32_bf16 v[14:17], v[160:163], v[216:219], v[14:17]
	v_mfma_f32_16x16x32_bf16 v[66:69], v[156:159], v[192:195], v[66:69]
	v_mfma_f32_16x16x32_bf16 v[62:65], v[164:167], v[192:195], v[62:65]
	v_mfma_f32_16x16x32_bf16 v[50:53], v[156:159], v[204:207], v[50:53]
	v_mfma_f32_16x16x32_bf16 v[46:49], v[164:167], v[204:207], v[46:49]
	v_mfma_f32_16x16x32_bf16 v[34:37], v[156:159], v[212:215], v[34:37]
	v_mfma_f32_16x16x32_bf16 v[30:33], v[164:167], v[212:215], v[30:33]
	v_mfma_f32_16x16x32_bf16 v[18:21], v[156:159], v[236:239], v[18:21]
	v_mfma_f32_16x16x32_bf16 v[14:17], v[164:167], v[236:239], v[14:17]
	s_setprio 0
	s_setprio 1
	v_mfma_f32_16x16x32_bf16 v[58:61], v[168:171], v[188:191], v[58:61]
	v_mfma_f32_16x16x32_bf16 v[54:57], v[180:183], v[188:191], v[54:57]
	v_mfma_f32_16x16x32_bf16 v[42:45], v[168:171], v[200:203], v[42:45]
	v_mfma_f32_16x16x32_bf16 v[38:41], v[180:183], v[200:203], v[38:41]
	v_mfma_f32_16x16x32_bf16 v[26:29], v[168:171], v[208:211], v[26:29]
	v_mfma_f32_16x16x32_bf16 v[22:25], v[180:183], v[208:211], v[22:25]
	v_mfma_f32_16x16x32_bf16 v[10:13], v[168:171], v[216:219], v[10:13]
	v_mfma_f32_16x16x32_bf16 v[6:9], v[180:183], v[216:219], v[6:9]
	v_mfma_f32_16x16x32_bf16 v[58:61], v[172:175], v[192:195], v[58:61]
	v_mfma_f32_16x16x32_bf16 v[54:57], v[184:187], v[192:195], v[54:57]
	v_mfma_f32_16x16x32_bf16 v[42:45], v[172:175], v[204:207], v[42:45]
	v_mfma_f32_16x16x32_bf16 v[38:41], v[184:187], v[204:207], v[38:41]
	v_mfma_f32_16x16x32_bf16 v[26:29], v[172:175], v[212:215], v[26:29]
	v_mfma_f32_16x16x32_bf16 v[22:25], v[184:187], v[212:215], v[22:25]
	v_mfma_f32_16x16x32_bf16 v[10:13], v[172:175], v[236:239], v[10:13]
	v_mfma_f32_16x16x32_bf16 v[6:9], v[184:187], v[236:239], v[6:9]
	s_setprio 0
	s_barrier
	s_add_i32 s93, 0, 0x18000
	v_add_u32_e32 v151, s93, v135
	s_add_i32 s97, 0, 0x1c000
	ds_read_b128 v[152:155], v151
	ds_read_b128 v[156:159], v151 offset:1024
	ds_read_b128 v[160:163], v151 offset:2048
	ds_read_b128 v[164:167], v151 offset:3072
	v_add_u32_e32 v151, s97, v135
	ds_read_b128 v[168:171], v151
	ds_read_b128 v[172:175], v151 offset:1024
	ds_read_b128 v[180:183], v151 offset:2048
	ds_read_b128 v[184:187], v151 offset:3072
	s_add_u32 s10, s10, 0x80000
	s_addc_u32 s11, s11, 0
	s_mov_b32 m0, s18
	v_lshl_add_u64 v[242:243], s[10:11], 0, v[144:145]
	ds_read_b128 v[188:191], v178 offset:32768
	ds_read_b128 v[192:195], v178 offset:33792
	ds_read_b128 v[200:203], v178 offset:34816
	ds_read_b128 v[204:207], v178 offset:35840
	ds_read_b128 v[208:211], v178 offset:36864
	ds_read_b128 v[212:215], v178 offset:37888
	ds_read_b128 v[216:219], v178 offset:38912
	ds_read_b128 v[236:239], v178 offset:39936
	global_load_lds_dwordx4 v[242:243], off
	v_lshl_add_u64 v[242:243], s[10:11], 0, v[136:137]
	s_mov_b32 m0, s19
	s_nop 0
	global_load_lds_dwordx4 v[242:243], off
	s_waitcnt vmcnt(8)
	s_waitcnt lgkmcnt(0)
	s_barrier
	s_setprio 1
	v_mfma_f32_16x16x32_bf16 v[130:133], v[152:155], v[188:191], v[130:133]
	v_mfma_f32_16x16x32_bf16 v[126:129], v[160:163], v[188:191], v[126:129]
	v_mfma_f32_16x16x32_bf16 v[114:117], v[152:155], v[200:203], v[114:117]
	v_mfma_f32_16x16x32_bf16 v[110:113], v[160:163], v[200:203], v[110:113]
	v_mfma_f32_16x16x32_bf16 v[98:101], v[152:155], v[208:211], v[98:101]
	v_mfma_f32_16x16x32_bf16 v[94:97], v[160:163], v[208:211], v[94:97]
	v_mfma_f32_16x16x32_bf16 v[82:85], v[152:155], v[216:219], v[82:85]
	v_mfma_f32_16x16x32_bf16 v[78:81], v[160:163], v[216:219], v[78:81]
	v_mfma_f32_16x16x32_bf16 v[130:133], v[156:159], v[192:195], v[130:133]
	v_mfma_f32_16x16x32_bf16 v[126:129], v[164:167], v[192:195], v[126:129]
	v_mfma_f32_16x16x32_bf16 v[114:117], v[156:159], v[204:207], v[114:117]
	v_mfma_f32_16x16x32_bf16 v[110:113], v[164:167], v[204:207], v[110:113]
	v_mfma_f32_16x16x32_bf16 v[98:101], v[156:159], v[212:215], v[98:101]
	v_mfma_f32_16x16x32_bf16 v[94:97], v[164:167], v[212:215], v[94:97]
	v_mfma_f32_16x16x32_bf16 v[82:85], v[156:159], v[236:239], v[82:85]
	v_mfma_f32_16x16x32_bf16 v[78:81], v[164:167], v[236:239], v[78:81]
	s_setprio 0
	s_setprio 1
	v_mfma_f32_16x16x32_bf16 v[122:125], v[168:171], v[188:191], v[122:125]
	v_mfma_f32_16x16x32_bf16 v[118:121], v[180:183], v[188:191], v[118:121]
	v_mfma_f32_16x16x32_bf16 v[106:109], v[168:171], v[200:203], v[106:109]
	v_mfma_f32_16x16x32_bf16 v[102:105], v[180:183], v[200:203], v[102:105]
	v_mfma_f32_16x16x32_bf16 v[90:93], v[168:171], v[208:211], v[90:93]
	v_mfma_f32_16x16x32_bf16 v[86:89], v[180:183], v[208:211], v[86:89]
	v_mfma_f32_16x16x32_bf16 v[74:77], v[168:171], v[216:219], v[74:77]
	v_mfma_f32_16x16x32_bf16 v[70:73], v[180:183], v[216:219], v[70:73]
	v_mfma_f32_16x16x32_bf16 v[122:125], v[172:175], v[192:195], v[122:125]
	v_mfma_f32_16x16x32_bf16 v[118:121], v[184:187], v[192:195], v[118:121]
	v_mfma_f32_16x16x32_bf16 v[106:109], v[172:175], v[204:207], v[106:109]
	v_mfma_f32_16x16x32_bf16 v[102:105], v[184:187], v[204:207], v[102:105]
	v_mfma_f32_16x16x32_bf16 v[90:93], v[172:175], v[212:215], v[90:93]
	v_mfma_f32_16x16x32_bf16 v[86:89], v[184:187], v[212:215], v[86:89]
	v_mfma_f32_16x16x32_bf16 v[74:77], v[172:175], v[236:239], v[74:77]
	v_mfma_f32_16x16x32_bf16 v[70:73], v[184:187], v[236:239], v[70:73]
	s_setprio 0
	s_barrier
; #define PG8_STAGE(bufoff, gbase, voff) do { _Pragma("unroll") for (int _i = 0; _i < 2; ++_i) \
;         __builtin_amdgcn_global_load_lds((const unsigned*)((const char*)(gbase) + (voff)[_i]), (PG8_LAS unsigned*)(lds + (bufoff) + ldsw + _i * 8192), 16, 0, 0); } while (0)
; #define PG8_LDA(dst, b, h) do { _Pragma("unroll") for (int m = 0; m < 4; ++m) _Pragma("unroll") for (int k = 0; k < 2; ++k) dst[m][k] = *(const PG8_LAS bf16x8*)(lds + PG8_SA(b, h) + aoff + m * 2048 + k * 1024); } while (0)
; #define PG8_MMA(ai, bj, At, Bt) do { __builtin_amdgcn_s_setprio(1); _Pragma("unroll") for (int m = 0; m < 4; ++m) _Pragma("unroll") for (int n = 0; n < 2; ++n) _Pragma("unroll") for (int k = 0; k < 2; ++k) \
;         acc[ai][bj][m][n] = __builtin_amdgcn_mfma_f32_16x16x32_bf16(Bt[n][k], At[m][k], acc[ai][bj][m][n], 0, 0, 0); __builtin_amdgcn_s_setprio(0); } while (0)
; #define PG8_WAIT_V(n) asm volatile("s_waitcnt vmcnt(" #n ")" ::: "memory")
; #define PG8_WAIT_L(n) asm volatile("s_waitcnt lgkmcnt(" #n ")" ::: "memory")
; #define PG8_BAR __builtin_amdgcn_s_barrier()
; #define PG8_SCHED __builtin_amdgcn_sched_barrier(0)
; template <class Epi, class Sched, bool ALIGN_EPI = false, bool SP2 = false>
; __device__ __forceinline__ void gemm_phase(PG8_LAS unsigned char* lds, const Gemm g, const Sched& S, const Epi& E) {
;     ...
;             PG8_LDA(At, 1, 1); PG8_STAGE(PG8_SB(1, 0), b3, voffB); PG8_STAGE(PG8_SB(1, 1), b3 + hstep, voffB); PG8_STAGE(PG8_SA(1, 0), a3, voffA);
;             PG8_WAIT_V(8); PG8_WAIT_L(0); PG8_BAR; PG8_MMA(1, 0, At, B0); PG8_MMA(1, 1, At, B1); PG8_BAR; PG8_SCHED;
	s_add_i32 s10, s93, s89
	v_lshl_add_u64 v[196:197], v[196:197], 0, s[64:65]
	s_mov_b32 m0, s10
	ds_read_b128 v[188:191], v178 offset:49152
	ds_read_b128 v[192:195], v178 offset:50176
	ds_read_b128 v[200:203], v178 offset:51200
	ds_read_b128 v[204:207], v178 offset:52224
	ds_read_b128 v[208:211], v178 offset:53248
	ds_read_b128 v[212:215], v178 offset:54272
	ds_read_b128 v[216:219], v178 offset:55296
	ds_read_b128 v[236:239], v178 offset:56320
	global_load_lds_dwordx4 v[196:197], off
	s_add_i32 m0, s10, 0x2000
	s_add_u32 s8, s8, 0x80080
	v_lshl_add_u64 v[196:197], v[228:229], 0, s[64:65]
	s_addc_u32 s9, s9, 0
	s_add_i32 s10, s97, s89
	global_load_lds_dwordx4 v[196:197], off
	v_lshl_add_u64 v[196:197], s[8:9], 0, v[142:143]
	s_mov_b32 m0, s10
	s_nop 0
	global_load_lds_dwordx4 v[196:197], off
	v_lshl_add_u64 v[196:197], s[8:9], 0, v[2:3]
	s_add_i32 m0, s10, 0x2000
	s_nop 0
	global_load_lds_dwordx4 v[196:197], off
	v_lshl_add_u64 v[196:197], v[230:231], 0, s[64:65]
	s_mov_b32 m0, s22
	s_nop 0
	global_load_lds_dwordx4 v[196:197], off
	v_lshl_add_u64 v[196:197], v[240:241], 0, s[64:65]
	s_mov_b32 m0, s23
	s_nop 0
	global_load_lds_dwordx4 v[196:197], off
	s_waitcnt vmcnt(8)
	s_waitcnt lgkmcnt(0)
	s_barrier
	s_setprio 1
	v_mfma_f32_16x16x32_bf16 v[66:69], v[152:155], v[188:191], v[66:69]
	v_mfma_f32_16x16x32_bf16 v[62:65], v[160:163], v[188:191], v[62:65]
	v_mfma_f32_16x16x32_bf16 v[50:53], v[152:155], v[200:203], v[50:53]
	v_mfma_f32_16x16x32_bf16 v[46:49], v[160:163], v[200:203], v[46:49]
	v_mfma_f32_16x16x32_bf16 v[34:37], v[152:155], v[208:211], v[34:37]
	v_mfma_f32_16x16x32_bf16 v[30:33], v[160:163], v[208:211], v[30:33]
	v_mfma_f32_16x16x32_bf16 v[18:21], v[152:155], v[216:219], v[18:21]
	v_mfma_f32_16x16x32_bf16 v[14:17], v[160:163], v[216:219], v[14:17]
	v_mfma_f32_16x16x32_bf16 v[66:69], v[156:159], v[192:195], v[66:69]
	v_mfma_f32_16x16x32_bf16 v[62:65], v[164:167], v[192:195], v[62:65]
	v_mfma_f32_16x16x32_bf16 v[50:53], v[156:159], v[204:207], v[50:53]
	v_mfma_f32_16x16x32_bf16 v[46:49], v[164:167], v[204:207], v[46:49]
	v_mfma_f32_16x16x32_bf16 v[34:37], v[156:159], v[212:215], v[34:37]
	v_mfma_f32_16x16x32_bf16 v[30:33], v[164:167], v[212:215], v[30:33]
	v_mfma_f32_16x16x32_bf16 v[18:21], v[156:159], v[236:239], v[18:21]
	v_mfma_f32_16x16x32_bf16 v[14:17], v[164:167], v[236:239], v[14:17]
	s_setprio 0
	s_setprio 1
	v_mfma_f32_16x16x32_bf16 v[58:61], v[168:171], v[188:191], v[58:61]
	v_mfma_f32_16x16x32_bf16 v[54:57], v[180:183], v[188:191], v[54:57]
	v_mfma_f32_16x16x32_bf16 v[42:45], v[168:171], v[200:203], v[42:45]
	v_mfma_f32_16x16x32_bf16 v[38:41], v[180:183], v[200:203], v[38:41]
	v_mfma_f32_16x16x32_bf16 v[26:29], v[168:171], v[208:211], v[26:29]
	v_mfma_f32_16x16x32_bf16 v[22:25], v[180:183], v[208:211], v[22:25]
	v_mfma_f32_16x16x32_bf16 v[10:13], v[168:171], v[216:219], v[10:13]
	v_mfma_f32_16x16x32_bf16 v[6:9], v[180:183], v[216:219], v[6:9]
	v_mfma_f32_16x16x32_bf16 v[58:61], v[172:175], v[192:195], v[58:61]
	v_mfma_f32_16x16x32_bf16 v[54:57], v[184:187], v[192:195], v[54:57]
	v_mfma_f32_16x16x32_bf16 v[42:45], v[172:175], v[204:207], v[42:45]
	v_mfma_f32_16x16x32_bf16 v[38:41], v[184:187], v[204:207], v[38:41]
	v_mfma_f32_16x16x32_bf16 v[26:29], v[172:175], v[212:215], v[26:29]
	v_mfma_f32_16x16x32_bf16 v[22:25], v[184:187], v[212:215], v[22:25]
	v_mfma_f32_16x16x32_bf16 v[10:13], v[172:175], v[236:239], v[10:13]
	v_mfma_f32_16x16x32_bf16 v[6:9], v[184:187], v[236:239], v[6:9]
	s_setprio 0
	s_barrier
	s_add_i32 s85, s85, 2
	s_add_u32 s6, s6, 0x100
	s_addc_u32 s7, s7, 0
	s_add_u32 s73, s73, 0x100
	s_addc_u32 s84, s84, 0
	s_cmp_gt_u32 s85, 29
	s_cbranch_scc0 .LBB0_161
	s_and_b64 vcc, exec, s[26:27]
	s_cbranch_vccz .LBB0_164
	s_barrier

; #define PG8_STAGE(bufoff, gbase, voff) do { _Pragma("unroll") for (int _i = 0; _i < 2; ++_i) \
;         __builtin_amdgcn_global_load_lds((const unsigned*)((const char*)(gbase) + (voff)[_i]), (PG8_LAS unsigned*)(lds + (bufoff) + ldsw + _i * 8192), 16, 0, 0); } while (0)
; #define PG8_LDA(dst, b, h) do { _Pragma("unroll") for (int m = 0; m < 4; ++m) _Pragma("unroll") for (int k = 0; k < 2; ++k) dst[m][k] = *(const PG8_LAS bf16x8*)(lds + PG8_SA(b, h) + aoff + m * 2048 + k * 1024); } while (0)
; #define PG8_LDB(dst, b, h) do { _Pragma("unroll") for (int n = 0; n < 2; ++n) _Pragma("unroll") for (int k = 0; k < 2; ++k) dst[n][k] = *(const PG8_LAS bf16x8*)(lds + PG8_SB(b, h) + boff + n * 2048 + k * 1024); } while (0)
; #define PG8_MMA(ai, bj, At, Bt) do { __builtin_amdgcn_s_setprio(1); _Pragma("unroll") for (int m = 0; m < 4; ++m) _Pragma("unroll") for (int n = 0; n < 2; ++n) _Pragma("unroll") for (int k = 0; k < 2; ++k) \
;         acc[ai][bj][m][n] = __builtin_amdgcn_mfma_f32_16x16x32_bf16(Bt[n][k], At[m][k], acc[ai][bj][m][n], 0, 0, 0); __builtin_amdgcn_s_setprio(0); } while (0)
; #define PG8_WAIT_V(n) asm volatile("s_waitcnt vmcnt(" #n ")" ::: "memory")
; #define PG8_WAIT_L(n) asm volatile("s_waitcnt lgkmcnt(" #n ")" ::: "memory")
; #define PG8_BAR __builtin_amdgcn_s_barrier()
; #define PG8_SCHED __builtin_amdgcn_sched_barrier(0)
; template <class Epi, class Sched, bool ALIGN_EPI = false, bool SP2 = false>
; __device__ __forceinline__ void gemm_phase(PG8_LAS unsigned char* lds, const Gemm g, const Sched& S, const Epi& E) {
;     ...
;             PG8_LDB(B0, 0, 0); PG8_LDB(B1, 0, 1); PG8_SCHED; PG8_LDA(At, 0, 0); PG8_STAGE(PG8_SA(1, 1), a1 + hstep, voffA);
;             PG8_WAIT_V(8); PG8_WAIT_L(0); PG8_BAR; PG8_MMA(0, 0, At, B0); PG8_MMA(0, 1, At, B1); PG8_BAR; PG8_SCHED;
;             PG8_LDA(At, 0, 1); PG8_STAGE(PG8_SB(0, 0), b2, voffB); PG8_STAGE(PG8_SB(0, 1), b2 + hstep, voffB); PG8_STAGE(PG8_SA(0, 0), a2, voffA);
;             PG8_WAIT_V(8); PG8_WAIT_L(0); PG8_BAR; PG8_MMA(1, 0, At, B0); PG8_MMA(1, 1, At, B1); PG8_BAR; PG8_SCHED;
.LBB0_1390:
	s_add_u32 s26, s8, 0xfffc0080
	s_addc_u32 s27, s9, -1
	s_add_i32 s90, 0, 0x10000
	s_cmp_eq_u32 s89, 12
	s_cselect_b32 s31, s15, s27
	s_cselect_b32 s30, s81, s26
	s_cselect_b32 s27, s17, s88
	s_cselect_b32 s26, s84, s85
	s_add_i32 s93, 0, 0x14000
	v_add_u32_e32 v154, s90, v135
	v_add_u32_e32 v170, s93, v135
	ds_read_b128 v[142:145], v154
	ds_read_b128 v[146:149], v154 offset:1024
	ds_read_b128 v[150:153], v154 offset:2048
	ds_read_b128 v[154:157], v154 offset:3072
	ds_read_b128 v[158:161], v170
	ds_read_b128 v[162:165], v170 offset:1024
	ds_read_b128 v[166:169], v170 offset:2048
	ds_read_b128 v[170:173], v170 offset:3072
	v_lshl_add_u64 v[174:175], s[8:9], 0, v[180:181]
	s_add_i32 m0, s44, 0xc000
	ds_read_b128 v[184:187], v236
	ds_read_b128 v[188:191], v236 offset:1024
	ds_read_b128 v[192:195], v236 offset:2048
	ds_read_b128 v[200:203], v236 offset:3072
	ds_read_b128 v[204:207], v236 offset:4096
	ds_read_b128 v[208:211], v236 offset:5120
	ds_read_b128 v[212:215], v236 offset:6144
	ds_read_b128 v[216:219], v236 offset:7168
	global_load_lds_dwordx4 v[174:175], off
	v_lshl_add_u64 v[174:175], s[8:9], 0, v[182:183]
	s_add_i32 m0, s44, 0xe000
	s_nop 0
	global_load_lds_dwordx4 v[174:175], off
	s_waitcnt vmcnt(8)
	s_waitcnt lgkmcnt(0)
	s_barrier
	s_setprio 1
	v_mfma_f32_16x16x32_bf16 v[130:133], v[142:145], v[184:187], v[130:133]
	v_mfma_f32_16x16x32_bf16 v[126:129], v[150:153], v[184:187], v[126:129]
	v_mfma_f32_16x16x32_bf16 v[114:117], v[142:145], v[192:195], v[114:117]
	v_mfma_f32_16x16x32_bf16 v[110:113], v[150:153], v[192:195], v[110:113]
	v_mfma_f32_16x16x32_bf16 v[98:101], v[142:145], v[204:207], v[98:101]
	v_mfma_f32_16x16x32_bf16 v[94:97], v[150:153], v[204:207], v[94:97]
	v_mfma_f32_16x16x32_bf16 v[82:85], v[142:145], v[212:215], v[82:85]
	v_mfma_f32_16x16x32_bf16 v[78:81], v[150:153], v[212:215], v[78:81]
	v_mfma_f32_16x16x32_bf16 v[130:133], v[146:149], v[188:191], v[130:133]
	v_mfma_f32_16x16x32_bf16 v[126:129], v[154:157], v[188:191], v[126:129]
	v_mfma_f32_16x16x32_bf16 v[114:117], v[146:149], v[200:203], v[114:117]
	v_mfma_f32_16x16x32_bf16 v[110:113], v[154:157], v[200:203], v[110:113]
	v_mfma_f32_16x16x32_bf16 v[98:101], v[146:149], v[208:211], v[98:101]
	v_mfma_f32_16x16x32_bf16 v[94:97], v[154:157], v[208:211], v[94:97]
	v_mfma_f32_16x16x32_bf16 v[82:85], v[146:149], v[216:219], v[82:85]
	v_mfma_f32_16x16x32_bf16 v[78:81], v[154:157], v[216:219], v[78:81]
	s_setprio 0
	s_setprio 1
	v_mfma_f32_16x16x32_bf16 v[122:125], v[158:161], v[184:187], v[122:125]
	v_mfma_f32_16x16x32_bf16 v[118:121], v[166:169], v[184:187], v[118:121]
	v_mfma_f32_16x16x32_bf16 v[106:109], v[158:161], v[192:195], v[106:109]
	v_mfma_f32_16x16x32_bf16 v[102:105], v[166:169], v[192:195], v[102:105]
	v_mfma_f32_16x16x32_bf16 v[90:93], v[158:161], v[204:207], v[90:93]
	v_mfma_f32_16x16x32_bf16 v[86:89], v[166:169], v[204:207], v[86:89]
	v_mfma_f32_16x16x32_bf16 v[74:77], v[158:161], v[212:215], v[74:77]
	v_mfma_f32_16x16x32_bf16 v[70:73], v[166:169], v[212:215], v[70:73]
	v_mfma_f32_16x16x32_bf16 v[122:125], v[162:165], v[188:191], v[122:125]
	v_mfma_f32_16x16x32_bf16 v[118:121], v[170:173], v[188:191], v[118:121]
	v_mfma_f32_16x16x32_bf16 v[106:109], v[162:165], v[200:203], v[106:109]
	v_mfma_f32_16x16x32_bf16 v[102:105], v[170:173], v[200:203], v[102:105]
	v_mfma_f32_16x16x32_bf16 v[90:93], v[162:165], v[208:211], v[90:93]
	v_mfma_f32_16x16x32_bf16 v[86:89], v[170:173], v[208:211], v[86:89]
	v_mfma_f32_16x16x32_bf16 v[74:77], v[162:165], v[216:219], v[74:77]
	v_mfma_f32_16x16x32_bf16 v[70:73], v[170:173], v[216:219], v[70:73]
	s_setprio 0
	s_barrier
	s_add_i32 s90, s90, s39
	v_lshl_add_u64 v[174:175], s[26:27], 0, v[176:177]
	s_mov_b32 m0, s90
	ds_read_b128 v[184:187], v236 offset:16384
	ds_read_b128 v[188:191], v236 offset:17408
	ds_read_b128 v[192:195], v236 offset:18432
	ds_read_b128 v[200:203], v236 offset:19456
	ds_read_b128 v[204:207], v236 offset:20480
	ds_read_b128 v[208:211], v236 offset:21504
	ds_read_b128 v[212:215], v236 offset:22528
	ds_read_b128 v[216:219], v236 offset:23552
	global_load_lds_dwordx4 v[174:175], off
	s_add_i32 m0, s90, 0x2000
	s_add_u32 s90, s26, 0x40000
	v_lshl_add_u64 v[196:197], s[26:27], 0, v[2:3]
	s_addc_u32 s91, s27, 0
	s_add_i32 s93, s93, s39
	global_load_lds_dwordx4 v[196:197], off
	v_lshl_add_u64 v[228:229], s[90:91], 0, v[176:177]
	s_mov_b32 m0, s93
	v_lshl_add_u64 v[230:231], s[30:31], 0, v[136:137]
	global_load_lds_dwordx4 v[228:229], off
	v_lshl_add_u64 v[228:229], s[90:91], 0, v[2:3]
	s_add_i32 m0, s93, 0x2000
	s_nop 0
	global_load_lds_dwordx4 v[228:229], off
	v_lshl_add_u64 v[228:229], s[30:31], 0, v[178:179]
	s_mov_b32 m0, s44
	s_nop 0
	global_load_lds_dwordx4 v[228:229], off
	s_mov_b32 m0, s45
	s_nop 0
	global_load_lds_dwordx4 v[230:231], off
	s_waitcnt vmcnt(8)
	s_waitcnt lgkmcnt(0)
	s_barrier
; #define PG8_STAGE(bufoff, gbase, voff) do { _Pragma("unroll") for (int _i = 0; _i < 2; ++_i) \
;         __builtin_amdgcn_global_load_lds((const unsigned*)((const char*)(gbase) + (voff)[_i]), (PG8_LAS unsigned*)(lds + (bufoff) + ldsw + _i * 8192), 16, 0, 0); } while (0)
; #define PG8_LDA(dst, b, h) do { _Pragma("unroll") for (int m = 0; m < 4; ++m) _Pragma("unroll") for (int k = 0; k < 2; ++k) dst[m][k] = *(const PG8_LAS bf16x8*)(lds + PG8_SA(b, h) + aoff + m * 2048 + k * 1024); } while (0)
; #define PG8_LDB(dst, b, h) do { _Pragma("unroll") for (int n = 0; n < 2; ++n) _Pragma("unroll") for (int k = 0; k < 2; ++k) dst[n][k] = *(const PG8_LAS bf16x8*)(lds + PG8_SB(b, h) + boff + n * 2048 + k * 1024); } while (0)
; #define PG8_MMA(ai, bj, At, Bt) do { __builtin_amdgcn_s_setprio(1); _Pragma("unroll") for (int m = 0; m < 4; ++m) _Pragma("unroll") for (int n = 0; n < 2; ++n) _Pragma("unroll") for (int k = 0; k < 2; ++k) \
;         acc[ai][bj][m][n] = __builtin_amdgcn_mfma_f32_16x16x32_bf16(Bt[n][k], At[m][k], acc[ai][bj][m][n], 0, 0, 0); __builtin_amdgcn_s_setprio(0); } while (0)
; #define PG8_WAIT_V(n) asm volatile("s_waitcnt vmcnt(" #n ")" ::: "memory")
; #define PG8_WAIT_L(n) asm volatile("s_waitcnt lgkmcnt(" #n ")" ::: "memory")
; #define PG8_BAR __builtin_amdgcn_s_barrier()
; #define PG8_SCHED __builtin_amdgcn_sched_barrier(0)
; template <class Epi, class Sched, bool ALIGN_EPI = false, bool SP2 = false>
; __device__ __forceinline__ void gemm_phase(PG8_LAS unsigned char* lds, const Gemm g, const Sched& S, const Epi& E) {
;     ...
;             PG8_WAIT_V(8); PG8_WAIT_L(0); PG8_BAR; PG8_MMA(1, 0, At, B0); PG8_MMA(1, 1, At, B1); PG8_BAR; PG8_SCHED;
;             PG8_LDB(B0, 1, 0); PG8_LDB(B1, 1, 1); PG8_SCHED; PG8_LDA(At, 1, 0); PG8_STAGE(PG8_SA(0, 1), a2 + hstep, voffA);
;             PG8_WAIT_V(8); PG8_WAIT_L(0); PG8_BAR; PG8_MMA(0, 0, At, B0); PG8_MMA(0, 1, At, B1); PG8_BAR; PG8_SCHED;
	s_setprio 1
	v_mfma_f32_16x16x32_bf16 v[66:69], v[142:145], v[184:187], v[66:69]
	v_mfma_f32_16x16x32_bf16 v[62:65], v[150:153], v[184:187], v[62:65]
	v_mfma_f32_16x16x32_bf16 v[50:53], v[142:145], v[192:195], v[50:53]
	v_mfma_f32_16x16x32_bf16 v[46:49], v[150:153], v[192:195], v[46:49]
	v_mfma_f32_16x16x32_bf16 v[34:37], v[142:145], v[204:207], v[34:37]
	v_mfma_f32_16x16x32_bf16 v[30:33], v[150:153], v[204:207], v[30:33]
	v_mfma_f32_16x16x32_bf16 v[18:21], v[142:145], v[212:215], v[18:21]
	v_mfma_f32_16x16x32_bf16 v[14:17], v[150:153], v[212:215], v[14:17]
	v_mfma_f32_16x16x32_bf16 v[66:69], v[146:149], v[188:191], v[66:69]
	v_mfma_f32_16x16x32_bf16 v[62:65], v[154:157], v[188:191], v[62:65]
	v_mfma_f32_16x16x32_bf16 v[50:53], v[146:149], v[200:203], v[50:53]
	v_mfma_f32_16x16x32_bf16 v[46:49], v[154:157], v[200:203], v[46:49]
	v_mfma_f32_16x16x32_bf16 v[34:37], v[146:149], v[208:211], v[34:37]
	v_mfma_f32_16x16x32_bf16 v[30:33], v[154:157], v[208:211], v[30:33]
	v_mfma_f32_16x16x32_bf16 v[18:21], v[146:149], v[216:219], v[18:21]
	v_mfma_f32_16x16x32_bf16 v[14:17], v[154:157], v[216:219], v[14:17]
	s_setprio 0
	s_setprio 1
	v_mfma_f32_16x16x32_bf16 v[58:61], v[158:161], v[184:187], v[58:61]
	v_mfma_f32_16x16x32_bf16 v[54:57], v[166:169], v[184:187], v[54:57]
	v_mfma_f32_16x16x32_bf16 v[42:45], v[158:161], v[192:195], v[42:45]
	v_mfma_f32_16x16x32_bf16 v[38:41], v[166:169], v[192:195], v[38:41]
	v_mfma_f32_16x16x32_bf16 v[26:29], v[158:161], v[204:207], v[26:29]
	v_mfma_f32_16x16x32_bf16 v[22:25], v[166:169], v[204:207], v[22:25]
	v_mfma_f32_16x16x32_bf16 v[10:13], v[158:161], v[212:215], v[10:13]
	v_mfma_f32_16x16x32_bf16 v[6:9], v[166:169], v[212:215], v[6:9]
	v_mfma_f32_16x16x32_bf16 v[58:61], v[162:165], v[188:191], v[58:61]
	v_mfma_f32_16x16x32_bf16 v[54:57], v[170:173], v[188:191], v[54:57]
	v_mfma_f32_16x16x32_bf16 v[42:45], v[162:165], v[200:203], v[42:45]
	v_mfma_f32_16x16x32_bf16 v[38:41], v[170:173], v[200:203], v[38:41]
	v_mfma_f32_16x16x32_bf16 v[26:29], v[162:165], v[208:211], v[26:29]
	v_mfma_f32_16x16x32_bf16 v[22:25], v[170:173], v[208:211], v[22:25]
	v_mfma_f32_16x16x32_bf16 v[10:13], v[162:165], v[216:219], v[10:13]
	v_mfma_f32_16x16x32_bf16 v[6:9], v[170:173], v[216:219], v[6:9]
	s_setprio 0
	s_barrier
	s_add_i32 s90, 0, 0x18000
	s_add_i32 s91, 0, 0x1c000
	v_add_u32_e32 v154, s90, v135
	v_add_u32_e32 v170, s91, v135
	ds_read_b128 v[142:145], v154
	ds_read_b128 v[146:149], v154 offset:1024
	ds_read_b128 v[150:153], v154 offset:2048
	ds_read_b128 v[154:157], v154 offset:3072
	ds_read_b128 v[158:161], v170
	ds_read_b128 v[162:165], v170 offset:1024
	ds_read_b128 v[166:169], v170 offset:2048
	ds_read_b128 v[170:173], v170 offset:3072
	s_add_u32 s30, s30, 0x40000
	s_addc_u32 s31, s31, 0
	s_mov_b32 m0, s60
	v_lshl_add_u64 v[238:239], s[30:31], 0, v[178:179]
	ds_read_b128 v[184:187], v236 offset:32768
	ds_read_b128 v[188:191], v236 offset:33792
	ds_read_b128 v[192:195], v236 offset:34816
	ds_read_b128 v[200:203], v236 offset:35840
	ds_read_b128 v[204:207], v236 offset:36864
	ds_read_b128 v[208:211], v236 offset:37888
	ds_read_b128 v[212:215], v236 offset:38912
	ds_read_b128 v[216:219], v236 offset:39936
	global_load_lds_dwordx4 v[238:239], off
	v_lshl_add_u64 v[238:239], s[30:31], 0, v[136:137]
	s_mov_b32 m0, s72
	s_nop 0
	global_load_lds_dwordx4 v[238:239], off
	s_waitcnt vmcnt(8)
	s_waitcnt lgkmcnt(0)
	s_barrier
	s_setprio 1
	v_mfma_f32_16x16x32_bf16 v[130:133], v[142:145], v[184:187], v[130:133]
	v_mfma_f32_16x16x32_bf16 v[126:129], v[150:153], v[184:187], v[126:129]
	v_mfma_f32_16x16x32_bf16 v[114:117], v[142:145], v[192:195], v[114:117]
	v_mfma_f32_16x16x32_bf16 v[110:113], v[150:153], v[192:195], v[110:113]
	v_mfma_f32_16x16x32_bf16 v[98:101], v[142:145], v[204:207], v[98:101]
	v_mfma_f32_16x16x32_bf16 v[94:97], v[150:153], v[204:207], v[94:97]
	v_mfma_f32_16x16x32_bf16 v[82:85], v[142:145], v[212:215], v[82:85]
	v_mfma_f32_16x16x32_bf16 v[78:81], v[150:153], v[212:215], v[78:81]
	v_mfma_f32_16x16x32_bf16 v[130:133], v[146:149], v[188:191], v[130:133]
	v_mfma_f32_16x16x32_bf16 v[126:129], v[154:157], v[188:191], v[126:129]
	v_mfma_f32_16x16x32_bf16 v[114:117], v[146:149], v[200:203], v[114:117]
	v_mfma_f32_16x16x32_bf16 v[110:113], v[154:157], v[200:203], v[110:113]
	v_mfma_f32_16x16x32_bf16 v[98:101], v[146:149], v[208:211], v[98:101]
	v_mfma_f32_16x16x32_bf16 v[94:97], v[154:157], v[208:211], v[94:97]
	v_mfma_f32_16x16x32_bf16 v[82:85], v[146:149], v[216:219], v[82:85]
	v_mfma_f32_16x16x32_bf16 v[78:81], v[154:157], v[216:219], v[78:81]
	s_setprio 0
	s_setprio 1
	v_mfma_f32_16x16x32_bf16 v[122:125], v[158:161], v[184:187], v[122:125]
	v_mfma_f32_16x16x32_bf16 v[118:121], v[166:169], v[184:187], v[118:121]
	v_mfma_f32_16x16x32_bf16 v[106:109], v[158:161], v[192:195], v[106:109]
	v_mfma_f32_16x16x32_bf16 v[102:105], v[166:169], v[192:195], v[102:105]
	v_mfma_f32_16x16x32_bf16 v[90:93], v[158:161], v[204:207], v[90:93]
	v_mfma_f32_16x16x32_bf16 v[86:89], v[166:169], v[204:207], v[86:89]
	v_mfma_f32_16x16x32_bf16 v[74:77], v[158:161], v[212:215], v[74:77]
	v_mfma_f32_16x16x32_bf16 v[70:73], v[166:169], v[212:215], v[70:73]
	v_mfma_f32_16x16x32_bf16 v[122:125], v[162:165], v[188:191], v[122:125]
	v_mfma_f32_16x16x32_bf16 v[118:121], v[170:173], v[188:191], v[118:121]
	v_mfma_f32_16x16x32_bf16 v[106:109], v[162:165], v[200:203], v[106:109]
	v_mfma_f32_16x16x32_bf16 v[102:105], v[170:173], v[200:203], v[102:105]
	v_mfma_f32_16x16x32_bf16 v[90:93], v[162:165], v[208:211], v[90:93]
	v_mfma_f32_16x16x32_bf16 v[86:89], v[170:173], v[208:211], v[86:89]
	v_mfma_f32_16x16x32_bf16 v[74:77], v[162:165], v[216:219], v[74:77]
	v_mfma_f32_16x16x32_bf16 v[70:73], v[170:173], v[216:219], v[70:73]
	s_setprio 0
	s_barrier
; #define PG8_STAGE(bufoff, gbase, voff) do { _Pragma("unroll") for (int _i = 0; _i < 2; ++_i) \
;         __builtin_amdgcn_global_load_lds((const unsigned*)((const char*)(gbase) + (voff)[_i]), (PG8_LAS unsigned*)(lds + (bufoff) + ldsw + _i * 8192), 16, 0, 0); } while (0)
; #define PG8_LDA(dst, b, h) do { _Pragma("unroll") for (int m = 0; m < 4; ++m) _Pragma("unroll") for (int k = 0; k < 2; ++k) dst[m][k] = *(const PG8_LAS bf16x8*)(lds + PG8_SA(b, h) + aoff + m * 2048 + k * 1024); } while (0)
; #define PG8_MMA(ai, bj, At, Bt) do { __builtin_amdgcn_s_setprio(1); _Pragma("unroll") for (int m = 0; m < 4; ++m) _Pragma("unroll") for (int n = 0; n < 2; ++n) _Pragma("unroll") for (int k = 0; k < 2; ++k) \
;         acc[ai][bj][m][n] = __builtin_amdgcn_mfma_f32_16x16x32_bf16(Bt[n][k], At[m][k], acc[ai][bj][m][n], 0, 0, 0); __builtin_amdgcn_s_setprio(0); } while (0)
; #define PG8_WAIT_V(n) asm volatile("s_waitcnt vmcnt(" #n ")" ::: "memory")
; #define PG8_WAIT_L(n) asm volatile("s_waitcnt lgkmcnt(" #n ")" ::: "memory")
; #define PG8_BAR __builtin_amdgcn_s_barrier()
; #define PG8_SCHED __builtin_amdgcn_sched_barrier(0)
; template <class Epi, class Sched, bool ALIGN_EPI = false, bool SP2 = false>
; __device__ __forceinline__ void gemm_phase(PG8_LAS unsigned char* lds, const Gemm g, const Sched& S, const Epi& E) {
;     ...
;             PG8_LDA(At, 1, 1); PG8_STAGE(PG8_SB(1, 0), b3, voffB); PG8_STAGE(PG8_SB(1, 1), b3 + hstep, voffB); PG8_STAGE(PG8_SA(1, 0), a3, voffA);
;             PG8_WAIT_V(8); PG8_WAIT_L(0); PG8_BAR; PG8_MMA(1, 0, At, B0); PG8_MMA(1, 1, At, B1); PG8_BAR; PG8_SCHED;
	s_add_i32 s30, s90, s39
	v_lshl_add_u64 v[174:175], v[174:175], 0, s[64:65]
	s_mov_b32 m0, s30
	ds_read_b128 v[184:187], v236 offset:49152
	ds_read_b128 v[188:191], v236 offset:50176
	ds_read_b128 v[192:195], v236 offset:51200
	ds_read_b128 v[200:203], v236 offset:52224
	ds_read_b128 v[204:207], v236 offset:53248
	ds_read_b128 v[208:211], v236 offset:54272
	ds_read_b128 v[212:215], v236 offset:55296
	ds_read_b128 v[216:219], v236 offset:56320
	global_load_lds_dwordx4 v[174:175], off
	s_add_i32 m0, s30, 0x2000
	s_add_u32 s26, s26, 0x40080
	v_lshl_add_u64 v[174:175], v[196:197], 0, s[64:65]
	s_addc_u32 s27, s27, 0
	s_add_i32 s30, s91, s39
	global_load_lds_dwordx4 v[174:175], off
	v_lshl_add_u64 v[174:175], s[26:27], 0, v[176:177]
	s_mov_b32 m0, s30
	s_nop 0
	global_load_lds_dwordx4 v[174:175], off
	v_lshl_add_u64 v[174:175], s[26:27], 0, v[2:3]
	s_add_i32 m0, s30, 0x2000
	s_nop 0
	global_load_lds_dwordx4 v[174:175], off
	v_lshl_add_u64 v[174:175], v[228:229], 0, s[64:65]
	s_mov_b32 m0, s73
	s_nop 0
	global_load_lds_dwordx4 v[174:175], off
	v_lshl_add_u64 v[174:175], v[230:231], 0, s[64:65]
	s_mov_b32 m0, s76
	s_nop 0
	global_load_lds_dwordx4 v[174:175], off
	s_waitcnt vmcnt(8)
	s_waitcnt lgkmcnt(0)
	s_barrier
	s_setprio 1
	v_mfma_f32_16x16x32_bf16 v[66:69], v[142:145], v[184:187], v[66:69]
	v_mfma_f32_16x16x32_bf16 v[62:65], v[150:153], v[184:187], v[62:65]
	v_mfma_f32_16x16x32_bf16 v[50:53], v[142:145], v[192:195], v[50:53]
	v_mfma_f32_16x16x32_bf16 v[46:49], v[150:153], v[192:195], v[46:49]
	v_mfma_f32_16x16x32_bf16 v[34:37], v[142:145], v[204:207], v[34:37]
	v_mfma_f32_16x16x32_bf16 v[30:33], v[150:153], v[204:207], v[30:33]
	v_mfma_f32_16x16x32_bf16 v[18:21], v[142:145], v[212:215], v[18:21]
	v_mfma_f32_16x16x32_bf16 v[14:17], v[150:153], v[212:215], v[14:17]
	v_mfma_f32_16x16x32_bf16 v[66:69], v[146:149], v[188:191], v[66:69]
	v_mfma_f32_16x16x32_bf16 v[62:65], v[154:157], v[188:191], v[62:65]
	v_mfma_f32_16x16x32_bf16 v[50:53], v[146:149], v[200:203], v[50:53]
	v_mfma_f32_16x16x32_bf16 v[46:49], v[154:157], v[200:203], v[46:49]
	v_mfma_f32_16x16x32_bf16 v[34:37], v[146:149], v[208:211], v[34:37]
	v_mfma_f32_16x16x32_bf16 v[30:33], v[154:157], v[208:211], v[30:33]
	v_mfma_f32_16x16x32_bf16 v[18:21], v[146:149], v[216:219], v[18:21]
	v_mfma_f32_16x16x32_bf16 v[14:17], v[154:157], v[216:219], v[14:17]
	s_setprio 0
	s_setprio 1
	v_mfma_f32_16x16x32_bf16 v[58:61], v[158:161], v[184:187], v[58:61]
	v_mfma_f32_16x16x32_bf16 v[54:57], v[166:169], v[184:187], v[54:57]
	v_mfma_f32_16x16x32_bf16 v[42:45], v[158:161], v[192:195], v[42:45]
	v_mfma_f32_16x16x32_bf16 v[38:41], v[166:169], v[192:195], v[38:41]
	v_mfma_f32_16x16x32_bf16 v[26:29], v[158:161], v[204:207], v[26:29]
	v_mfma_f32_16x16x32_bf16 v[22:25], v[166:169], v[204:207], v[22:25]
	v_mfma_f32_16x16x32_bf16 v[10:13], v[158:161], v[212:215], v[10:13]
	v_mfma_f32_16x16x32_bf16 v[6:9], v[166:169], v[212:215], v[6:9]
	v_mfma_f32_16x16x32_bf16 v[58:61], v[162:165], v[188:191], v[58:61]
	v_mfma_f32_16x16x32_bf16 v[54:57], v[170:173], v[188:191], v[54:57]
	v_mfma_f32_16x16x32_bf16 v[42:45], v[162:165], v[200:203], v[42:45]
	v_mfma_f32_16x16x32_bf16 v[38:41], v[170:173], v[200:203], v[38:41]
	v_mfma_f32_16x16x32_bf16 v[26:29], v[162:165], v[208:211], v[26:29]
	v_mfma_f32_16x16x32_bf16 v[22:25], v[170:173], v[208:211], v[22:25]
	v_mfma_f32_16x16x32_bf16 v[10:13], v[162:165], v[216:219], v[10:13]
	v_mfma_f32_16x16x32_bf16 v[6:9], v[170:173], v[216:219], v[6:9]
	s_setprio 0
	s_barrier
	s_add_i32 s89, s89, 2
	s_add_u32 s8, s8, 0x100
	s_addc_u32 s9, s9, 0
	s_add_u32 s85, s85, 0x100
	s_addc_u32 s88, s88, 0
	s_cmp_gt_u32 s89, 13
	s_cbranch_scc0 .LBB0_1390
	s_and_b64 vcc, exec, s[12:13]
	s_cbranch_vccz .LBB0_1393
	s_barrier

; #define PG8_STAGE(bufoff, gbase, voff) do { _Pragma("unroll") for (int _i = 0; _i < 2; ++_i) \
;         __builtin_amdgcn_global_load_lds((const unsigned*)((const char*)(gbase) + (voff)[_i]), (PG8_LAS unsigned*)(lds + (bufoff) + ldsw + _i * 8192), 16, 0, 0); } while (0)
; #define PG8_LDA(dst, b, h) do { _Pragma("unroll") for (int m = 0; m < 4; ++m) _Pragma("unroll") for (int k = 0; k < 2; ++k) dst[m][k] = *(const PG8_LAS bf16x8*)(lds + PG8_SA(b, h) + aoff + m * 2048 + k * 1024); } while (0)
; #define PG8_LDB(dst, b, h) do { _Pragma("unroll") for (int n = 0; n < 2; ++n) _Pragma("unroll") for (int k = 0; k < 2; ++k) dst[n][k] = *(const PG8_LAS bf16x8*)(lds + PG8_SB(b, h) + boff + n * 2048 + k * 1024); } while (0)
; #define PG8_MMA(ai, bj, At, Bt) do { __builtin_amdgcn_s_setprio(1); _Pragma("unroll") for (int m = 0; m < 4; ++m) _Pragma("unroll") for (int n = 0; n < 2; ++n) _Pragma("unroll") for (int k = 0; k < 2; ++k) \
;         acc[ai][bj][m][n] = __builtin_amdgcn_mfma_f32_16x16x32_bf16(Bt[n][k], At[m][k], acc[ai][bj][m][n], 0, 0, 0); __builtin_amdgcn_s_setprio(0); } while (0)
; #define PG8_WAIT_V(n) asm volatile("s_waitcnt vmcnt(" #n ")" ::: "memory")
; #define PG8_WAIT_L(n) asm volatile("s_waitcnt lgkmcnt(" #n ")" ::: "memory")
; #define PG8_BAR __builtin_amdgcn_s_barrier()
; #define PG8_SCHED __builtin_amdgcn_sched_barrier(0)
; template <class Epi, class Sched, bool ALIGN_EPI = false, bool SP2 = false>
; __device__ __forceinline__ void gemm_phase(PG8_LAS unsigned char* lds, const Gemm g, const Sched& S, const Epi& E) {
;     ...
;             PG8_LDB(B0, 0, 0); PG8_LDB(B1, 0, 1); PG8_SCHED; PG8_LDA(At, 0, 0); PG8_STAGE(PG8_SA(1, 1), a1 + hstep, voffA);
;             PG8_WAIT_V(8); PG8_WAIT_L(0); PG8_BAR; PG8_MMA(0, 0, At, B0); PG8_MMA(0, 1, At, B1); PG8_BAR; PG8_SCHED;
;             PG8_LDA(At, 0, 1); PG8_STAGE(PG8_SB(0, 0), b2, voffB); PG8_STAGE(PG8_SB(0, 1), b2 + hstep, voffB); PG8_STAGE(PG8_SA(0, 0), a2, voffA);
;             PG8_WAIT_V(8); PG8_WAIT_L(0); PG8_BAR; PG8_MMA(1, 0, At, B0); PG8_MMA(1, 1, At, B1); PG8_BAR; PG8_SCHED;
.LBB0_1506:
	s_add_u32 s22, s8, 0xfff80080
	s_addc_u32 s23, s9, -1
	s_add_i32 s69, 0, 0x10000
	s_cmp_eq_u32 s15, 28
	s_cselect_b32 s81, s39, s23
	s_cselect_b32 s80, vcc_lo, s22
	s_cselect_b32 s77, s31, s14
	s_cselect_b32 s76, vcc_hi, s93
	s_add_i32 s60, 0, 0x14000
	v_add_u32_e32 v78, s69, v135
	v_add_u32_e32 v170, s60, v135
	ds_read_b128 v[66:69], v78
	ds_read_b128 v[70:73], v78 offset:1024
	ds_read_b128 v[74:77], v78 offset:2048
	ds_read_b128 v[78:81], v78 offset:3072
	ds_read_b128 v[158:161], v170
	ds_read_b128 v[162:165], v170 offset:1024
	ds_read_b128 v[166:169], v170 offset:2048
	ds_read_b128 v[170:173], v170 offset:3072
	v_lshl_add_u64 v[212:213], s[8:9], 0, v[200:201]
	s_add_i32 m0, s85, 0xc000
	ds_read_b128 v[174:177], v215
	ds_read_b128 v[178:181], v215 offset:1024
	ds_read_b128 v[182:185], v215 offset:2048
	ds_read_b128 v[186:189], v215 offset:3072
	ds_read_b128 v[190:193], v215 offset:4096
	ds_read_b128 v[194:197], v215 offset:5120
	ds_read_b128 v[204:207], v215 offset:6144
	ds_read_b128 v[208:211], v215 offset:7168
	global_load_lds_dwordx4 v[212:213], off
	v_lshl_add_u64 v[212:213], s[8:9], 0, v[202:203]
	s_add_i32 m0, s85, 0xe000
	s_nop 0
	global_load_lds_dwordx4 v[212:213], off
	s_waitcnt vmcnt(8)
	s_waitcnt lgkmcnt(0)
	s_barrier
	s_setprio 1
	v_mfma_f32_16x16x32_bf16 v[154:157], v[66:69], v[174:177], v[154:157]
	v_mfma_f32_16x16x32_bf16 v[150:153], v[74:77], v[174:177], v[150:153]
	v_mfma_f32_16x16x32_bf16 v[142:145], v[66:69], v[182:185], v[142:145]
	v_mfma_f32_16x16x32_bf16 v[126:129], v[74:77], v[182:185], v[126:129]
	v_mfma_f32_16x16x32_bf16 v[114:117], v[66:69], v[190:193], v[114:117]
	v_mfma_f32_16x16x32_bf16 v[110:113], v[74:77], v[190:193], v[110:113]
	v_mfma_f32_16x16x32_bf16 v[102:105], v[66:69], v[204:207], v[102:105]
	v_mfma_f32_16x16x32_bf16 v[94:97], v[74:77], v[204:207], v[94:97]
	v_mfma_f32_16x16x32_bf16 v[154:157], v[70:73], v[178:181], v[154:157]
	v_mfma_f32_16x16x32_bf16 v[150:153], v[78:81], v[178:181], v[150:153]
	v_mfma_f32_16x16x32_bf16 v[142:145], v[70:73], v[186:189], v[142:145]
	v_mfma_f32_16x16x32_bf16 v[126:129], v[78:81], v[186:189], v[126:129]
	v_mfma_f32_16x16x32_bf16 v[114:117], v[70:73], v[194:197], v[114:117]
	v_mfma_f32_16x16x32_bf16 v[110:113], v[78:81], v[194:197], v[110:113]
	v_mfma_f32_16x16x32_bf16 v[102:105], v[70:73], v[208:211], v[102:105]
	v_mfma_f32_16x16x32_bf16 v[94:97], v[78:81], v[208:211], v[94:97]
	s_setprio 0
	s_setprio 1
	v_mfma_f32_16x16x32_bf16 v[146:149], v[158:161], v[174:177], v[146:149]
	v_mfma_f32_16x16x32_bf16 v[130:133], v[166:169], v[174:177], v[130:133]
	v_mfma_f32_16x16x32_bf16 v[122:125], v[158:161], v[182:185], v[122:125]
	v_mfma_f32_16x16x32_bf16 v[118:121], v[166:169], v[182:185], v[118:121]
	v_mfma_f32_16x16x32_bf16 v[106:109], v[158:161], v[190:193], v[106:109]
	v_mfma_f32_16x16x32_bf16 v[98:101], v[166:169], v[190:193], v[98:101]
	v_mfma_f32_16x16x32_bf16 v[90:93], v[158:161], v[204:207], v[90:93]
	v_mfma_f32_16x16x32_bf16 v[86:89], v[166:169], v[204:207], v[86:89]
	v_mfma_f32_16x16x32_bf16 v[146:149], v[162:165], v[178:181], v[146:149]
	v_mfma_f32_16x16x32_bf16 v[130:133], v[170:173], v[178:181], v[130:133]
	v_mfma_f32_16x16x32_bf16 v[122:125], v[162:165], v[186:189], v[122:125]
	v_mfma_f32_16x16x32_bf16 v[118:121], v[170:173], v[186:189], v[118:121]
	v_mfma_f32_16x16x32_bf16 v[106:109], v[162:165], v[194:197], v[106:109]
	v_mfma_f32_16x16x32_bf16 v[98:101], v[170:173], v[194:197], v[98:101]
	v_mfma_f32_16x16x32_bf16 v[90:93], v[162:165], v[208:211], v[90:93]
	v_mfma_f32_16x16x32_bf16 v[86:89], v[170:173], v[208:211], v[86:89]
	s_setprio 0
	s_barrier
	s_add_i32 s22, s69, s35
	v_lshl_add_u64 v[212:213], s[76:77], 0, v[136:137]
	s_mov_b32 m0, s22
	ds_read_b128 v[174:177], v215 offset:16384
	ds_read_b128 v[178:181], v215 offset:17408
	ds_read_b128 v[182:185], v215 offset:18432
	ds_read_b128 v[186:189], v215 offset:19456
	ds_read_b128 v[190:193], v215 offset:20480
	ds_read_b128 v[194:197], v215 offset:21504
	ds_read_b128 v[204:207], v215 offset:22528
	ds_read_b128 v[208:211], v215 offset:23552
	global_load_lds_dwordx4 v[212:213], off
	s_add_i32 m0, s22, 0x2000
	s_add_u32 s22, s76, 0x80000
	v_lshl_add_u64 v[216:217], s[76:77], 0, v[2:3]
	s_addc_u32 s23, s77, 0
	s_add_i32 s60, s60, s35
	global_load_lds_dwordx4 v[216:217], off
	v_lshl_add_u64 v[218:219], s[22:23], 0, v[136:137]
	s_mov_b32 m0, s60
	v_lshl_add_u64 v[228:229], s[80:81], 0, v[2:3]
	global_load_lds_dwordx4 v[218:219], off
	v_lshl_add_u64 v[218:219], s[22:23], 0, v[2:3]
	s_add_i32 m0, s60, 0x2000
	s_nop 0
	global_load_lds_dwordx4 v[218:219], off
	v_lshl_add_u64 v[218:219], s[80:81], 0, v[136:137]
	s_mov_b32 m0, s85
	s_nop 0
	global_load_lds_dwordx4 v[218:219], off
	s_mov_b32 m0, s88
	s_nop 0
	global_load_lds_dwordx4 v[228:229], off
	s_waitcnt vmcnt(8)
	s_waitcnt lgkmcnt(0)
	s_barrier
; #define PG8_STAGE(bufoff, gbase, voff) do { _Pragma("unroll") for (int _i = 0; _i < 2; ++_i) \
;         __builtin_amdgcn_global_load_lds((const unsigned*)((const char*)(gbase) + (voff)[_i]), (PG8_LAS unsigned*)(lds + (bufoff) + ldsw + _i * 8192), 16, 0, 0); } while (0)
; #define PG8_LDA(dst, b, h) do { _Pragma("unroll") for (int m = 0; m < 4; ++m) _Pragma("unroll") for (int k = 0; k < 2; ++k) dst[m][k] = *(const PG8_LAS bf16x8*)(lds + PG8_SA(b, h) + aoff + m * 2048 + k * 1024); } while (0)
; #define PG8_LDB(dst, b, h) do { _Pragma("unroll") for (int n = 0; n < 2; ++n) _Pragma("unroll") for (int k = 0; k < 2; ++k) dst[n][k] = *(const PG8_LAS bf16x8*)(lds + PG8_SB(b, h) + boff + n * 2048 + k * 1024); } while (0)
; #define PG8_MMA(ai, bj, At, Bt) do { __builtin_amdgcn_s_setprio(1); _Pragma("unroll") for (int m = 0; m < 4; ++m) _Pragma("unroll") for (int n = 0; n < 2; ++n) _Pragma("unroll") for (int k = 0; k < 2; ++k) \
;         acc[ai][bj][m][n] = __builtin_amdgcn_mfma_f32_16x16x32_bf16(Bt[n][k], At[m][k], acc[ai][bj][m][n], 0, 0, 0); __builtin_amdgcn_s_setprio(0); } while (0)
; #define PG8_WAIT_V(n) asm volatile("s_waitcnt vmcnt(" #n ")" ::: "memory")
; #define PG8_WAIT_L(n) asm volatile("s_waitcnt lgkmcnt(" #n ")" ::: "memory")
; #define PG8_BAR __builtin_amdgcn_s_barrier()
; #define PG8_SCHED __builtin_amdgcn_sched_barrier(0)
; template <class Epi, class Sched, bool ALIGN_EPI = false, bool SP2 = false>
; __device__ __forceinline__ void gemm_phase(PG8_LAS unsigned char* lds, const Gemm g, const Sched& S, const Epi& E) {
;     ...
;             PG8_WAIT_V(8); PG8_WAIT_L(0); PG8_BAR; PG8_MMA(1, 0, At, B0); PG8_MMA(1, 1, At, B1); PG8_BAR; PG8_SCHED;
;             PG8_LDB(B0, 1, 0); PG8_LDB(B1, 1, 1); PG8_SCHED; PG8_LDA(At, 1, 0); PG8_STAGE(PG8_SA(0, 1), a2 + hstep, voffA);
;             PG8_WAIT_V(8); PG8_WAIT_L(0); PG8_BAR; PG8_MMA(0, 0, At, B0); PG8_MMA(0, 1, At, B1); PG8_BAR; PG8_SCHED;
	s_setprio 1
	v_mfma_f32_16x16x32_bf16 v[82:85], v[66:69], v[174:177], v[82:85]
	v_mfma_f32_16x16x32_bf16 v[62:65], v[74:77], v[174:177], v[62:65]
	v_mfma_f32_16x16x32_bf16 v[54:57], v[66:69], v[182:185], v[54:57]
	v_mfma_f32_16x16x32_bf16 v[46:49], v[74:77], v[182:185], v[46:49]
	v_mfma_f32_16x16x32_bf16 v[34:37], v[66:69], v[190:193], v[34:37]
	v_mfma_f32_16x16x32_bf16 v[30:33], v[74:77], v[190:193], v[30:33]
	v_mfma_f32_16x16x32_bf16 v[22:25], v[66:69], v[204:207], v[22:25]
	v_mfma_f32_16x16x32_bf16 v[14:17], v[74:77], v[204:207], v[14:17]
	v_mfma_f32_16x16x32_bf16 v[82:85], v[70:73], v[178:181], v[82:85]
	v_mfma_f32_16x16x32_bf16 v[62:65], v[78:81], v[178:181], v[62:65]
	v_mfma_f32_16x16x32_bf16 v[54:57], v[70:73], v[186:189], v[54:57]
	v_mfma_f32_16x16x32_bf16 v[46:49], v[78:81], v[186:189], v[46:49]
	v_mfma_f32_16x16x32_bf16 v[34:37], v[70:73], v[194:197], v[34:37]
	v_mfma_f32_16x16x32_bf16 v[30:33], v[78:81], v[194:197], v[30:33]
	v_mfma_f32_16x16x32_bf16 v[22:25], v[70:73], v[208:211], v[22:25]
	v_mfma_f32_16x16x32_bf16 v[14:17], v[78:81], v[208:211], v[14:17]
	s_setprio 0
	s_setprio 1
	v_mfma_f32_16x16x32_bf16 v[58:61], v[158:161], v[174:177], v[58:61]
	v_mfma_f32_16x16x32_bf16 v[50:53], v[166:169], v[174:177], v[50:53]
	v_mfma_f32_16x16x32_bf16 v[42:45], v[158:161], v[182:185], v[42:45]
	v_mfma_f32_16x16x32_bf16 v[38:41], v[166:169], v[182:185], v[38:41]
	v_mfma_f32_16x16x32_bf16 v[26:29], v[158:161], v[190:193], v[26:29]
	v_mfma_f32_16x16x32_bf16 v[18:21], v[166:169], v[190:193], v[18:21]
	v_mfma_f32_16x16x32_bf16 v[10:13], v[158:161], v[204:207], v[10:13]
	v_mfma_f32_16x16x32_bf16 v[6:9], v[166:169], v[204:207], v[6:9]
	v_mfma_f32_16x16x32_bf16 v[58:61], v[162:165], v[178:181], v[58:61]
	v_mfma_f32_16x16x32_bf16 v[50:53], v[170:173], v[178:181], v[50:53]
	v_mfma_f32_16x16x32_bf16 v[42:45], v[162:165], v[186:189], v[42:45]
	v_mfma_f32_16x16x32_bf16 v[38:41], v[170:173], v[186:189], v[38:41]
	v_mfma_f32_16x16x32_bf16 v[26:29], v[162:165], v[194:197], v[26:29]
	v_mfma_f32_16x16x32_bf16 v[18:21], v[170:173], v[194:197], v[18:21]
	v_mfma_f32_16x16x32_bf16 v[10:13], v[162:165], v[208:211], v[10:13]
	v_mfma_f32_16x16x32_bf16 v[6:9], v[170:173], v[208:211], v[6:9]
	s_setprio 0
	s_barrier
	s_add_i32 s60, 0, 0x18000
	s_add_i32 s69, 0, 0x1c000
	v_add_u32_e32 v78, s60, v135
	v_add_u32_e32 v170, s69, v135
	ds_read_b128 v[66:69], v78
	ds_read_b128 v[70:73], v78 offset:1024
	ds_read_b128 v[74:77], v78 offset:2048
	ds_read_b128 v[78:81], v78 offset:3072
	ds_read_b128 v[158:161], v170
	ds_read_b128 v[162:165], v170 offset:1024
	ds_read_b128 v[166:169], v170 offset:2048
	ds_read_b128 v[170:173], v170 offset:3072
	s_add_u32 s22, s80, 0x80000
	s_addc_u32 s23, s81, 0
	s_mov_b32 m0, s89
	v_lshl_add_u64 v[230:231], s[22:23], 0, v[136:137]
	ds_read_b128 v[174:177], v215 offset:32768
	ds_read_b128 v[178:181], v215 offset:33792
	ds_read_b128 v[182:185], v215 offset:34816
	ds_read_b128 v[186:189], v215 offset:35840
	ds_read_b128 v[190:193], v215 offset:36864
	ds_read_b128 v[194:197], v215 offset:37888
	ds_read_b128 v[204:207], v215 offset:38912
	ds_read_b128 v[208:211], v215 offset:39936
	global_load_lds_dwordx4 v[230:231], off
	v_lshl_add_u64 v[230:231], s[22:23], 0, v[2:3]
	s_mov_b32 m0, s90
	s_nop 0
	global_load_lds_dwordx4 v[230:231], off
	s_waitcnt vmcnt(8)
	s_waitcnt lgkmcnt(0)
	s_barrier
	s_setprio 1
	v_mfma_f32_16x16x32_bf16 v[154:157], v[66:69], v[174:177], v[154:157]
	v_mfma_f32_16x16x32_bf16 v[150:153], v[74:77], v[174:177], v[150:153]
	v_mfma_f32_16x16x32_bf16 v[142:145], v[66:69], v[182:185], v[142:145]
	v_mfma_f32_16x16x32_bf16 v[126:129], v[74:77], v[182:185], v[126:129]
	v_mfma_f32_16x16x32_bf16 v[114:117], v[66:69], v[190:193], v[114:117]
	v_mfma_f32_16x16x32_bf16 v[110:113], v[74:77], v[190:193], v[110:113]
	v_mfma_f32_16x16x32_bf16 v[102:105], v[66:69], v[204:207], v[102:105]
	v_mfma_f32_16x16x32_bf16 v[94:97], v[74:77], v[204:207], v[94:97]
	v_mfma_f32_16x16x32_bf16 v[154:157], v[70:73], v[178:181], v[154:157]
	v_mfma_f32_16x16x32_bf16 v[150:153], v[78:81], v[178:181], v[150:153]
	v_mfma_f32_16x16x32_bf16 v[142:145], v[70:73], v[186:189], v[142:145]
	v_mfma_f32_16x16x32_bf16 v[126:129], v[78:81], v[186:189], v[126:129]
	v_mfma_f32_16x16x32_bf16 v[114:117], v[70:73], v[194:197], v[114:117]
	v_mfma_f32_16x16x32_bf16 v[110:113], v[78:81], v[194:197], v[110:113]
	v_mfma_f32_16x16x32_bf16 v[102:105], v[70:73], v[208:211], v[102:105]
	v_mfma_f32_16x16x32_bf16 v[94:97], v[78:81], v[208:211], v[94:97]
	s_setprio 0
	s_setprio 1
	v_mfma_f32_16x16x32_bf16 v[146:149], v[158:161], v[174:177], v[146:149]
	v_mfma_f32_16x16x32_bf16 v[130:133], v[166:169], v[174:177], v[130:133]
	v_mfma_f32_16x16x32_bf16 v[122:125], v[158:161], v[182:185], v[122:125]
	v_mfma_f32_16x16x32_bf16 v[118:121], v[166:169], v[182:185], v[118:121]
	v_mfma_f32_16x16x32_bf16 v[106:109], v[158:161], v[190:193], v[106:109]
	v_mfma_f32_16x16x32_bf16 v[98:101], v[166:169], v[190:193], v[98:101]
	v_mfma_f32_16x16x32_bf16 v[90:93], v[158:161], v[204:207], v[90:93]
	v_mfma_f32_16x16x32_bf16 v[86:89], v[166:169], v[204:207], v[86:89]
	v_mfma_f32_16x16x32_bf16 v[146:149], v[162:165], v[178:181], v[146:149]
	v_mfma_f32_16x16x32_bf16 v[130:133], v[170:173], v[178:181], v[130:133]
	v_mfma_f32_16x16x32_bf16 v[122:125], v[162:165], v[186:189], v[122:125]
	v_mfma_f32_16x16x32_bf16 v[118:121], v[170:173], v[186:189], v[118:121]
	v_mfma_f32_16x16x32_bf16 v[106:109], v[162:165], v[194:197], v[106:109]
	v_mfma_f32_16x16x32_bf16 v[98:101], v[170:173], v[194:197], v[98:101]
	v_mfma_f32_16x16x32_bf16 v[90:93], v[162:165], v[208:211], v[90:93]
	v_mfma_f32_16x16x32_bf16 v[86:89], v[170:173], v[208:211], v[86:89]
	s_setprio 0
	s_barrier
; #define PG8_STAGE(bufoff, gbase, voff) do { _Pragma("unroll") for (int _i = 0; _i < 2; ++_i) \
;         __builtin_amdgcn_global_load_lds((const unsigned*)((const char*)(gbase) + (voff)[_i]), (PG8_LAS unsigned*)(lds + (bufoff) + ldsw + _i * 8192), 16, 0, 0); } while (0)
; #define PG8_LDA(dst, b, h) do { _Pragma("unroll") for (int m = 0; m < 4; ++m) _Pragma("unroll") for (int k = 0; k < 2; ++k) dst[m][k] = *(const PG8_LAS bf16x8*)(lds + PG8_SA(b, h) + aoff + m * 2048 + k * 1024); } while (0)
; #define PG8_MMA(ai, bj, At, Bt) do { __builtin_amdgcn_s_setprio(1); _Pragma("unroll") for (int m = 0; m < 4; ++m) _Pragma("unroll") for (int n = 0; n < 2; ++n) _Pragma("unroll") for (int k = 0; k < 2; ++k) \
;         acc[ai][bj][m][n] = __builtin_amdgcn_mfma_f32_16x16x32_bf16(Bt[n][k], At[m][k], acc[ai][bj][m][n], 0, 0, 0); __builtin_amdgcn_s_setprio(0); } while (0)
; #define PG8_WAIT_V(n) asm volatile("s_waitcnt vmcnt(" #n ")" ::: "memory")
; #define PG8_WAIT_L(n) asm volatile("s_waitcnt lgkmcnt(" #n ")" ::: "memory")
; #define PG8_BAR __builtin_amdgcn_s_barrier()
; #define PG8_SCHED __builtin_amdgcn_sched_barrier(0)
; template <class Epi, class Sched, bool ALIGN_EPI = false, bool SP2 = false>
; __device__ __forceinline__ void gemm_phase(PG8_LAS unsigned char* lds, const Gemm g, const Sched& S, const Epi& E) {
;     ...
;             PG8_LDA(At, 1, 1); PG8_STAGE(PG8_SB(1, 0), b3, voffB); PG8_STAGE(PG8_SB(1, 1), b3 + hstep, voffB); PG8_STAGE(PG8_SA(1, 0), a3, voffA);
;             PG8_WAIT_V(8); PG8_WAIT_L(0); PG8_BAR; PG8_MMA(1, 0, At, B0); PG8_MMA(1, 1, At, B1); PG8_BAR; PG8_SCHED;
	s_add_i32 s22, s60, s35
	v_lshl_add_u64 v[212:213], v[212:213], 0, s[64:65]
	s_mov_b32 m0, s22
	ds_read_b128 v[174:177], v215 offset:49152
	ds_read_b128 v[178:181], v215 offset:50176
	ds_read_b128 v[182:185], v215 offset:51200
	ds_read_b128 v[186:189], v215 offset:52224
	ds_read_b128 v[190:193], v215 offset:53248
	ds_read_b128 v[194:197], v215 offset:54272
	ds_read_b128 v[204:207], v215 offset:55296
	ds_read_b128 v[208:211], v215 offset:56320
	global_load_lds_dwordx4 v[212:213], off
	s_add_i32 m0, s22, 0x2000
	s_add_u32 s22, s76, 0x80080
	v_lshl_add_u64 v[212:213], v[216:217], 0, s[64:65]
	s_addc_u32 s23, s77, 0
	s_add_i32 s60, s69, s35
	global_load_lds_dwordx4 v[212:213], off
	v_lshl_add_u64 v[212:213], s[22:23], 0, v[136:137]
	s_mov_b32 m0, s60
	s_nop 0
	global_load_lds_dwordx4 v[212:213], off
	v_lshl_add_u64 v[212:213], s[22:23], 0, v[2:3]
	s_add_i32 m0, s60, 0x2000
	s_nop 0
	global_load_lds_dwordx4 v[212:213], off
	v_lshl_add_u64 v[212:213], v[218:219], 0, s[64:65]
	s_mov_b32 m0, s91
	s_nop 0
	global_load_lds_dwordx4 v[212:213], off
	v_lshl_add_u64 v[212:213], v[228:229], 0, s[64:65]
	s_mov_b32 m0, s16
	s_nop 0
	global_load_lds_dwordx4 v[212:213], off
	s_waitcnt vmcnt(8)
	s_waitcnt lgkmcnt(0)
	s_barrier
	s_setprio 1
	v_mfma_f32_16x16x32_bf16 v[82:85], v[66:69], v[174:177], v[82:85]
	v_mfma_f32_16x16x32_bf16 v[62:65], v[74:77], v[174:177], v[62:65]
	v_mfma_f32_16x16x32_bf16 v[54:57], v[66:69], v[182:185], v[54:57]
	v_mfma_f32_16x16x32_bf16 v[46:49], v[74:77], v[182:185], v[46:49]
	v_mfma_f32_16x16x32_bf16 v[34:37], v[66:69], v[190:193], v[34:37]
	v_mfma_f32_16x16x32_bf16 v[30:33], v[74:77], v[190:193], v[30:33]
	v_mfma_f32_16x16x32_bf16 v[22:25], v[66:69], v[204:207], v[22:25]
	v_mfma_f32_16x16x32_bf16 v[14:17], v[74:77], v[204:207], v[14:17]
	v_mfma_f32_16x16x32_bf16 v[82:85], v[70:73], v[178:181], v[82:85]
	v_mfma_f32_16x16x32_bf16 v[62:65], v[78:81], v[178:181], v[62:65]
	v_mfma_f32_16x16x32_bf16 v[54:57], v[70:73], v[186:189], v[54:57]
	v_mfma_f32_16x16x32_bf16 v[46:49], v[78:81], v[186:189], v[46:49]
	v_mfma_f32_16x16x32_bf16 v[34:37], v[70:73], v[194:197], v[34:37]
	v_mfma_f32_16x16x32_bf16 v[30:33], v[78:81], v[194:197], v[30:33]
	v_mfma_f32_16x16x32_bf16 v[22:25], v[70:73], v[208:211], v[22:25]
	v_mfma_f32_16x16x32_bf16 v[14:17], v[78:81], v[208:211], v[14:17]
	s_setprio 0
	s_setprio 1
	v_mfma_f32_16x16x32_bf16 v[58:61], v[158:161], v[174:177], v[58:61]
	v_mfma_f32_16x16x32_bf16 v[50:53], v[166:169], v[174:177], v[50:53]
	v_mfma_f32_16x16x32_bf16 v[42:45], v[158:161], v[182:185], v[42:45]
	v_mfma_f32_16x16x32_bf16 v[38:41], v[166:169], v[182:185], v[38:41]
	v_mfma_f32_16x16x32_bf16 v[26:29], v[158:161], v[190:193], v[26:29]
	v_mfma_f32_16x16x32_bf16 v[18:21], v[166:169], v[190:193], v[18:21]
	v_mfma_f32_16x16x32_bf16 v[10:13], v[158:161], v[204:207], v[10:13]
	v_mfma_f32_16x16x32_bf16 v[6:9], v[166:169], v[204:207], v[6:9]
	v_mfma_f32_16x16x32_bf16 v[58:61], v[162:165], v[178:181], v[58:61]
	v_mfma_f32_16x16x32_bf16 v[50:53], v[170:173], v[178:181], v[50:53]
	v_mfma_f32_16x16x32_bf16 v[42:45], v[162:165], v[186:189], v[42:45]
	v_mfma_f32_16x16x32_bf16 v[38:41], v[170:173], v[186:189], v[38:41]
	v_mfma_f32_16x16x32_bf16 v[26:29], v[162:165], v[194:197], v[26:29]
	v_mfma_f32_16x16x32_bf16 v[18:21], v[170:173], v[194:197], v[18:21]
	v_mfma_f32_16x16x32_bf16 v[10:13], v[162:165], v[208:211], v[10:13]
	v_mfma_f32_16x16x32_bf16 v[6:9], v[170:173], v[208:211], v[6:9]
	s_setprio 0
	s_barrier
	s_add_i32 s15, s15, 2
	s_add_u32 s8, s8, 0x100
	s_addc_u32 s9, s9, 0
	s_add_u32 s93, s93, 0x100
	s_addc_u32 s14, s14, 0
	s_cmp_gt_u32 s15, 29
	s_cbranch_scc0 .LBB0_1506
	v_readlane_b32 s8, v254, 26
	v_readlane_b32 s9, v254, 27
	s_and_b64 vcc, exec, s[8:9]
	s_cbranch_vccz .LBB0_1509
	s_barrier
